# XCC-local seams via per-workgroup arrival flags (plain L2-resident stores + one L2-served 32-lane poll) instead of an atomic counter
# speedup vs baseline: 1.0971x; 1.0261x over previous
.Lxb_have:
	v_readfirstlane_b32 s10, v0
	v_readfirstlane_b32 s11, v1
	v_readlane_b32 s8, v240, 60
	s_add_i32 s101, s101, 1
	v_mov_b32_e32 v2, 1
	s_nop 1
	v_mov_b32_e32 v4, s8
	ds_read_b32 v4, v4 offset:8
	v_readlane_b32 s8, v240, 0
	s_nop 0
	s_lshl_b32 s9, s8, 6
	s_add_u32 s9, s9, 0x4000
	s_add_u32 s14, s6, s9
	s_addc_u32 s15, s7, 0
	s_waitcnt lgkmcnt(0)
	v_readfirstlane_b32 s9, v4
	s_cmp_eq_u32 s9, 1
	s_cbranch_scc0 .Lxb_grid
	s_mov_b32 s9, 0x3cfdf3f4
	s_bitcmp1_b32 s9, s70
	s_cbranch_scc0 .Lxb_grid
	s_and_b32 s9, s8, 7
	s_lshl_b32 s9, s9, 8
	s_add_u32 s9, s9, 0x12000
	s_add_u32 s12, s6, s9
	s_addc_u32 s13, s7, 0
	s_lshr_b32 s9, s8, 3
	s_lshl_b32 s9, s9, 2
	v_mov_b32_e32 v3, s9
	v_mov_b32_e32 v2, s101
	global_store_dword v3, v2, s[12:13]
	buffer_inv sc1
	s_mov_b32 s9, 0
	s_mov_b32 exec_lo, -1
	s_mov_b32 exec_hi, 0
	v_mbcnt_lo_u32_b32 v3, -1, 0
	v_lshlrev_b32_e32 v3, 2, v3
.Lxb_lpoll:
	global_load_dword v4, v3, s[12:13] sc1
	s_add_i32 s9, s9, 1
	s_waitcnt vmcnt(0)
	v_cmp_gt_u32_e32 vcc, s101, v4
	s_cbranch_vccz .Lxb_ldone
	s_cmp_gt_u32 s9, 0x2000
	s_cbranch_scc1 .Lxb_ldone
	s_sleep 1
	s_branch .Lxb_lpoll
.Lxb_ldone:
	s_mov_b64 exec, 1
	s_branch .Lxb_done
.Lxb_grid:
	s_add_i32 s100, s100, 1
	s_mul_i32 s10, s10, s100
	s_mul_i32 s11, s11, s100
	s_add_u32 s12, s6, s3
	s_addc_u32 s13, s7, 0
	global_atomic_add v3, v196, v2, s[12:13] offset:1024 sc0
	buffer_inv sc1
	s_mov_b32 s9, 0
	s_waitcnt vmcnt(1)
	v_add_u32_e32 v3, 1, v3
	v_cmp_eq_u32_e32 vcc, s10, v3
	s_cbranch_vccz .Lxb_poll
	buffer_wbl2 sc1
	v_readlane_b32 s12, v240, 46
	v_readlane_b32 s13, v240, 47
	s_waitcnt vmcnt(0)
	s_nop 3
	global_atomic_add v3, v165, v2, s[12:13] sc0
	s_waitcnt vmcnt(0)
	v_add_u32_e32 v3, 1, v3
	v_cmp_eq_u32_e32 vcc, s11, v3
	s_cbranch_vccz .Lxb_poll
	s_add_u32 s12, s6, 0x4000
	s_addc_u32 s13, s7, 0
	s_mov_b64 exec, -1
	v_mbcnt_lo_u32_b32 v3, -1, 0
	v_mbcnt_hi_u32_b32 v3, -1, v3
	v_mov_b32_e32 v2, 1
	v_lshlrev_b32_e32 v3, 6, v3
	v_add_u32_e32 v4, 0x1000, v3
	v_add_u32_e32 v5, 0x2000, v3
	v_add_u32_e32 v6, 0x3000, v3
	global_atomic_add v3, v2, s[12:13]
	global_atomic_add v4, v2, s[12:13]
	global_atomic_add v5, v2, s[12:13]
	global_atomic_add v6, v2, s[12:13]
	s_waitcnt vmcnt(4)
	s_mov_b64 exec, 1
	s_branch .LBB0_463
